# differential-attention loop PV tail: six one-at-a-time V^T ds_reads -> rolling 4-deep buffer with counted lgkmcnt
# speedup vs baseline: 1.0094x; 1.0006x over previous
; DI void qk_tile(f32x4 (&st)[4], const char* sK, const bf16x8 (&qf)[2], int lr, int g) {
; #pragma unroll
;   for (int kt = 0; kt < 4; ++kt) {
;     st[kt] = (f32x4){0.f, 0.f, 0.f, 0.f};
; #pragma unroll
;     for (int ks = 0; ks < 2; ++ks) st[kt] = MFMA16(*(const bf16x8*)(sK + (kt * 16 + lr) * 128 + (((ks * 4 + g) ^ ((lr >> 1) & 7)) << 4)), qf[ks], st[kt]);
;   }
; }
; DI void qk_tile2(f32x4 (&sa)[4], f32x4 (&sb)[4], const char* sK, const bf16x8 (&qa)[2], const bf16x8 (&qb)[2], int lr, int g) {
; #pragma unroll
;   for (int kt = 0; kt < 4; ++kt) {
;     const bf16x8 k0 = *(const bf16x8*)(sK + (kt * 16 + lr) * 128 + ((g ^ ((lr >> 1) & 7)) << 4)), k1 = *(const bf16x8*)(sK + (kt * 16 + lr) * 128 + (((4 + g) ^ ((lr >> 1) & 7)) << 4));
;     sa[kt] = MFMA16(k0, qa[0], ((f32x4){0.f, 0.f, 0.f, 0.f})); sb[kt] = MFMA16(k0, qb[0], ((f32x4){0.f, 0.f, 0.f, 0.f}));
;     sa[kt] = MFMA16(k1, qa[1], sa[kt]); sb[kt] = MFMA16(k1, qb[1], sb[kt]);
;   }
; }
; DI float softmax_step(f32x4 (&st)[4], float& m, float& lsum) {
;   float mx = fmaxf(fmaxf(fmaxf(st[0][0], st[0][1]), fmaxf(st[0][2], st[0][3])), fmaxf(fmaxf(st[1][0], st[1][1]), fmaxf(st[1][2], st[1][3])));
;   mx = fmaxf(mx, fmaxf(fmaxf(fmaxf(st[2][0], st[2][1]), fmaxf(st[2][2], st[2][3])), fmaxf(fmaxf(st[3][0], st[3][1]), fmaxf(st[3][2], st[3][3]))));
;   mx = fmaxf(mx, __shfl_xor(mx, 16)); mx = fmaxf(mx, __shfl_xor(mx, 32));
;   const float mn = fmaxf(m, mx);
;   const float mu = mn == -INFINITY ? 0.f : mn;
;   const float alpha = __builtin_amdgcn_exp2f(m - mu);
;   float ps = 0.f;
; #pragma unroll
;   for (int kt = 0; kt < 4; ++kt)
; #pragma unroll
;     for (int j = 0; j < 4; ++j) { const float p = __builtin_amdgcn_exp2f(st[kt][j] - mu); st[kt][j] = p; ps += p; }
;   lsum = lsum * alpha + ps; m = mn;
;   return alpha;
; }
; DI void attn_A(const Params& P, int l, int b, int head, int qt, float lam, char* smem, bf16_t* ybase, size_t ypitch) {
;     ...
;   for (int n = 0; n <= qt; ++n) {
;     const char* sb = smem + (n & 1) * STAGE;
;     if (n < qt) {
;       const bf16_t* kn = kbase + (size_t)(n + 1) * 64 * PW;
;       gload2(rk0, kn, PW, tid); gload2(rk1, kn + 64, PW, tid); gload4(rv, vbase + (n + 1) * 64, SEQ, tid);
;     }
;     f32x4 s0[4], s1[4];
;     qk_tile(s0, sb, qf0, lr, g);
;     qk_tile(s1, sb + 9216, qf1, lr, g);
;     const float a0 = softmax_step(s0, m0, l0), a1 = softmax_step(s1, m1, l1);
.LBB0_810:
	s_bitcmp1_b32 s8, 0
	s_cselect_b32 s9, 0x9000, 0
	v_or_b32_e32 v120, s9, v199
	v_add_u32_e32 v219, v120, v200
	v_add_u32_e32 v202, v120, v201
	ds_read_b128 v[112:115], v219
	ds_read_b128 v[116:119], v219 offset:2048
	ds_read_b128 v[120:123], v202
	ds_read_b128 v[124:127], v202 offset:2048
	s_waitcnt lgkmcnt(3)
	v_mfma_f32_16x16x32_f16 v[112:115], v[112:115], v[0:3], 0
	s_mov_b32 s9, 0xff800000
	s_waitcnt lgkmcnt(1)
	v_mfma_f32_16x16x32_f16 v[136:139], v[120:123], v[8:11], v[112:115]
	s_nop 4
	ds_read_b128 v[112:115], v219 offset:4096
	ds_read_b128 v[120:123], v202 offset:4096
	v_mfma_f32_16x16x32_f16 v[116:119], v[116:119], v[0:3], 0
	s_waitcnt lgkmcnt(1)
	v_mfma_f32_16x16x32_f16 v[112:115], v[112:115], v[0:3], 0
	v_mfma_f32_16x16x32_f16 v[128:131], v[124:127], v[8:11], v[116:119]
	s_nop 4
	ds_read_b128 v[116:119], v219 offset:6144
	ds_read_b128 v[140:143], v219 offset:9216
	ds_read_b128 v[124:127], v202 offset:6144
	ds_read_b128 v[144:147], v202 offset:9216
	ds_read_b128 v[204:207], v219 offset:11264
	ds_read_b128 v[210:213], v219 offset:13312
	s_waitcnt lgkmcnt(6)
	v_mfma_f32_16x16x32_f16 v[132:135], v[120:123], v[8:11], v[112:115]
	ds_read_b128 v[120:123], v202 offset:11264
	ds_read_b128 v[220:223], v202 offset:13312
	ds_read_b128 v[224:227], v219 offset:15360
	s_waitcnt lgkmcnt(8)
	v_mfma_f32_16x16x32_f16 v[112:115], v[116:119], v[0:3], 0
	v_max_f32_e32 v116, v138, v139
	v_max3_f32 v203, v136, v137, v116
	v_max_f32_e32 v116, v130, v131
	s_waitcnt lgkmcnt(6)
	v_mfma_f32_16x16x32_f16 v[124:127], v[124:127], v[8:11], v[112:115]
	v_mfma_f32_16x16x32_f16 v[112:115], v[140:143], v[4:7], 0
	v_max3_f32 v140, v128, v129, v116
	v_max_f32_e32 v141, v132, v133
	s_waitcnt lgkmcnt(4)
	v_mfma_f32_16x16x32_f16 v[116:119], v[204:207], v[4:7], 0
	v_max_f32_e32 v142, v134, v135
	s_waitcnt lgkmcnt(2)
	v_mfma_f32_16x16x32_f16 v[116:119], v[120:123], v[12:15], v[116:119]
	v_max_f32_e32 v120, v126, v127
	v_max3_f32 v143, v124, v125, v120
	v_max3_f32 v141, v141, v142, v143
	v_mfma_f32_16x16x32_f16 v[112:115], v[144:147], v[12:15], v[112:115]
	v_max3_f32 v144, v203, v140, v141
	ds_bpermute_b32 v145, v189, v144
	ds_read_b128 v[140:143], v202 offset:15360
	v_mfma_f32_16x16x32_f16 v[120:123], v[210:213], v[4:7], 0
	s_waitcnt lgkmcnt(1)
	v_max_f32_e32 v203, v144, v145
	ds_bpermute_b32 v204, v188, v203
	v_mfma_f32_16x16x32_f16 v[144:147], v[224:227], v[4:7], 0
	s_waitcnt lgkmcnt(1)
	v_mfma_f32_16x16x32_f16 v[232:235], v[140:143], v[12:15], v[144:147]
	v_mfma_f32_16x16x32_f16 v[120:123], v[220:223], v[12:15], v[120:123]
	s_waitcnt lgkmcnt(0)
	s_nop 3
	v_max3_f32 v146, v209, v203, v204
	v_cmp_neq_f32_e32 vcc, s9, v146
	ds_read_b128 v[220:223], v219 offset:32768
	ds_read_b128 v[224:227], v219 offset:18432
	ds_read_b128 v[228:231], v202 offset:18432
	v_cndmask_b32_e32 v141, 0, v146, vcc
	v_sub_f32_e32 v136, v136, v141
	v_sub_f32_e32 v128, v128, v141
	v_exp_f32_e32 v203, v136
	v_sub_f32_e32 v136, v137, v141
	v_exp_f32_e32 v207, v128
	v_sub_f32_e32 v128, v129, v141
	v_sub_f32_e32 v129, v131, v141
	v_exp_f32_e32 v204, v136
	v_sub_f32_e32 v136, v138, v141
	v_exp_f32_e32 v208, v128
	v_sub_f32_e32 v128, v130, v141
	v_exp_f32_e32 v130, v129
	v_sub_f32_e32 v129, v132, v141
	v_exp_f32_e32 v205, v136
	v_sub_f32_e32 v136, v139, v141
	v_exp_f32_e32 v132, v129
	v_sub_f32_e32 v129, v133, v141
	v_exp_f32_e32 v206, v136
	v_exp_f32_e32 v136, v129
	v_sub_f32_e32 v129, v134, v141
	v_exp_f32_e32 v134, v129
	v_sub_f32_e32 v129, v135, v141
	v_exp_f32_e32 v138, v129
	v_max_f32_e32 v129, v114, v115
	v_max_f32_e32 v131, v118, v119
	v_max_f32_e32 v133, v120, v121
	v_max_f32_e32 v135, v122, v123
	v_max_f32_e32 v137, v234, v235
	v_max3_f32 v137, v232, v233, v137
	v_max3_f32 v129, v112, v113, v129
	v_max3_f32 v131, v116, v117, v131
	v_max3_f32 v133, v133, v135, v137
	v_max3_f32 v129, v129, v131, v133
	v_mov_b32_e32 v131, v129
	v_sub_f32_e32 v125, v125, v141
	v_exp_f32_e32 v140, v125
	v_sub_f32_e32 v125, v126, v141
	v_exp_f32_e32 v126, v125
	s_waitcnt lgkmcnt(0)
	s_nop 1
	v_permlane16_swap_b32_e32 v129, v131
	v_max_f32_e32 v125, v129, v131
	v_mov_b32_e32 v129, v125
	v_sub_f32_e32 v127, v127, v141
	v_exp_f32_e32 v142, v127
	v_sub_f32_e32 v127, v209, v141
	v_exp_f32_e32 v128, v128
	s_waitcnt lgkmcnt(0)
; #define MFMA16(a, b, c) __builtin_amdgcn_mfma_f32_16x16x32_f16((a), (b), (c), 0, 0, 0)
; DI float softmax_step(f32x4 (&st)[4], float& m, float& lsum) {
;   float mx = fmaxf(fmaxf(fmaxf(st[0][0], st[0][1]), fmaxf(st[0][2], st[0][3])), fmaxf(fmaxf(st[1][0], st[1][1]), fmaxf(st[1][2], st[1][3])));
;   mx = fmaxf(mx, fmaxf(fmaxf(fmaxf(st[2][0], st[2][1]), fmaxf(st[2][2], st[2][3])), fmaxf(fmaxf(st[3][0], st[3][1]), fmaxf(st[3][2], st[3][3]))));
;   mx = fmaxf(mx, __shfl_xor(mx, 16)); mx = fmaxf(mx, __shfl_xor(mx, 32));
;   const float mn = fmaxf(m, mx);
;   const float mu = mn == -INFINITY ? 0.f : mn;
;   const float alpha = __builtin_amdgcn_exp2f(m - mu);
;   float ps = 0.f;
; #pragma unroll
;   for (int kt = 0; kt < 4; ++kt)
; #pragma unroll
;     for (int j = 0; j < 4; ++j) { const float p = __builtin_amdgcn_exp2f(st[kt][j] - mu); st[kt][j] = p; ps += p; }
;   lsum = lsum * alpha + ps; m = mn;
;   return alpha;
; }
; DI void attn_A(const Params& P, int l, int b, int head, int qt, float lam, char* smem, bf16_t* ybase, size_t ypitch) {
;     ...
;     const float a0 = softmax_step(s0, m0, l0), a1 = softmax_step(s1, m1, l1);
; #pragma unroll
;     for (int i = 0; i < 8; ++i) { o0[i] *= a0; o1[i] *= a1; }
; #pragma unroll
;     for (int kk = 0; kk < 2; ++kk) {
;       const bf16x8 p0 = pack8(s0[2 * kk], s0[2 * kk + 1]), p1 = pack8(s1[2 * kk], s1[2 * kk + 1]);
; #pragma unroll
;       for (int dt = 0; dt < 8; ++dt) {
;         const bf16x8 vf = vfrag(sb + 18432, dt, kk, lr, g);
;         o0[dt] = MFMA16(vf, p0, o0[dt]);
;         o1[dt] = MFMA16(vf, p1, o1[dt]);
;       }
;     }
	s_nop 1
	v_permlane32_swap_b32_e32 v125, v129
	v_max3_f32 v147, v215, v125, v129
	v_cmp_neq_f32_e32 vcc, s9, v147
	v_exp_f32_e32 v144, v127
	ds_read_b128 v[236:239], v219 offset:20480
	v_cndmask_b32_e32 v143, 0, v147, vcc
	v_sub_f32_e32 v112, v112, v143
	v_exp_f32_e32 v209, v112
	v_sub_f32_e32 v112, v113, v143
	v_exp_f32_e32 v210, v112
	v_sub_f32_e32 v112, v114, v143
	v_exp_f32_e32 v211, v112
	v_sub_f32_e32 v112, v115, v143
	v_exp_f32_e32 v212, v112
	v_sub_f32_e32 v112, v116, v143
	v_exp_f32_e32 v213, v112
	v_sub_f32_e32 v112, v117, v143
	v_exp_f32_e32 v214, v112
	v_sub_f32_e32 v112, v118, v143
	v_exp_f32_e32 v129, v112
	v_sub_f32_e32 v112, v119, v143
	v_exp_f32_e32 v131, v112
	v_sub_f32_e32 v112, v120, v143
	v_exp_f32_e32 v133, v112
	v_sub_f32_e32 v112, v121, v143
	v_exp_f32_e32 v137, v112
	v_sub_f32_e32 v112, v122, v143
	v_exp_f32_e32 v135, v112
	v_sub_f32_e32 v112, v215, v143
	v_exp_f32_e32 v120, v112
	v_sub_f32_e32 v121, v123, v143
	v_cvt_pk_f16_f32 v112, v203, v204
	v_cvt_pk_f16_f32 v113, v205, v206
	v_cvt_pk_f16_f32 v114, v207, v208
	v_cvt_pk_f16_f32 v116, v209, v210
	v_cvt_pk_f16_f32 v117, v211, v212
	v_cvt_pk_f16_f32 v118, v213, v214
	v_pk_mul_f32 v[94:95], v[94:95], v[144:145] op_sel_hi:[1,0]
	v_pk_mul_f32 v[92:93], v[92:93], v[144:145] op_sel_hi:[1,0]
	v_cvt_pk_f16_f32 v115, v128, v130
	v_pk_mul_f32 v[102:103], v[102:103], v[120:121] op_sel_hi:[1,0]
	v_pk_mul_f32 v[100:101], v[100:101], v[120:121] op_sel_hi:[1,0]
	v_cvt_pk_f16_f32 v119, v129, v131
	v_mfma_f32_16x16x32_f16 v[92:95], v[224:227], v[112:115], v[92:95]
	v_exp_f32_e32 v139, v121
	v_pk_mul_f32 v[98:99], v[98:99], v[120:121] op_sel_hi:[1,0]
	v_pk_mul_f32 v[96:97], v[96:97], v[120:121] op_sel_hi:[1,0]
	v_mfma_f32_16x16x32_f16 v[100:103], v[224:227], v[116:119], v[100:103]
	ds_read_b128 v[224:227], v219 offset:22528
	v_sub_f32_e32 v121, v232, v143
	v_pk_mul_f32 v[90:91], v[90:91], v[120:121] op_sel_hi:[1,0]
	v_pk_mul_f32 v[88:89], v[88:89], v[120:121] op_sel_hi:[1,0]
	v_exp_f32_e32 v125, v121
	v_pk_mul_f32 v[82:83], v[82:83], v[120:121] op_sel_hi:[1,0]
	v_pk_mul_f32 v[80:81], v[80:81], v[120:121] op_sel_hi:[1,0]
	v_sub_f32_e32 v121, v233, v143
	v_sub_f32_e32 v124, v124, v141
	v_pk_mul_f32 v[74:75], v[74:75], v[120:121] op_sel_hi:[1,0]
	v_pk_mul_f32 v[72:73], v[72:73], v[120:121] op_sel_hi:[1,0]
	v_exp_f32_e32 v141, v121
	v_pk_mul_f32 v[62:63], v[62:63], v[120:121] op_sel_hi:[1,0]
	v_pk_mul_f32 v[60:61], v[60:61], v[120:121] op_sel_hi:[1,0]
	v_sub_f32_e32 v121, v234, v143
	v_exp_f32_e32 v127, v121
	v_pk_mul_f32 v[50:51], v[50:51], v[120:121] op_sel_hi:[1,0]
	v_pk_mul_f32 v[48:49], v[48:49], v[120:121] op_sel_hi:[1,0]
	v_sub_f32_e32 v121, v235, v143
	v_pk_mul_f32 v[86:87], v[86:87], v[144:145] op_sel_hi:[1,0]
	v_pk_mul_f32 v[84:85], v[84:85], v[144:145] op_sel_hi:[1,0]
	v_pk_mul_f32 v[78:79], v[78:79], v[144:145] op_sel_hi:[1,0]
	v_pk_mul_f32 v[76:77], v[76:77], v[144:145] op_sel_hi:[1,0]
	v_pk_mul_f32 v[106:107], v[106:107], v[144:145] op_sel_hi:[1,0]
	v_pk_mul_f32 v[104:105], v[104:105], v[144:145] op_sel_hi:[1,0]
	v_pk_mul_f32 v[110:111], v[110:111], v[120:121] op_sel_hi:[1,0]
	v_pk_mul_f32 v[108:109], v[108:109], v[120:121] op_sel_hi:[1,0]
	v_mfma_f32_16x16x32_f16 v[104:107], v[220:223], v[112:115], v[104:107]
	v_mul_f32_e64 v70, v70, v144
	v_mul_f32_e64 v71, v71, v144
	v_pk_mul_f32 v[68:69], v[68:69], v[144:145] op_sel_hi:[1,0]
	v_pk_mul_f32 v[58:59], v[58:59], v[144:145] op_sel_hi:[1,0]
	v_mfma_f32_16x16x32_f16 v[108:111], v[220:223], v[116:119], v[108:111]
	ds_read_b128 v[220:223], v202 offset:20480
	v_pk_mul_f32 v[56:57], v[56:57], v[144:145] op_sel_hi:[1,0]
	v_exp_f32_e32 v124, v124
	s_waitcnt lgkmcnt(2)
	v_mfma_f32_16x16x32_f16 v[84:87], v[236:239], v[112:115], v[84:87]
	v_exp_f32_e32 v143, v121
	v_pk_mul_f32 v[46:47], v[46:47], v[144:145] op_sel_hi:[1,0]
	v_pk_mul_f32 v[44:45], v[44:45], v[144:145] op_sel_hi:[1,0]
	v_mfma_f32_16x16x32_f16 v[96:99], v[236:239], v[116:119], v[96:99]
	ds_read_b128 v[236:239], v219 offset:24576
	v_pk_mul_f32 v[42:43], v[42:43], v[144:145] op_sel_hi:[1,0]
	v_pk_mul_f32 v[40:41], v[40:41], v[144:145] op_sel_hi:[1,0]
	s_waitcnt lgkmcnt(2)
	v_mfma_f32_16x16x32_f16 v[76:79], v[224:227], v[112:115], v[76:79]
	s_andn2_b64 vcc, exec, s[6:7]
	v_mfma_f32_16x16x32_f16 v[88:91], v[224:227], v[116:119], v[88:91]
	ds_read_b128 v[224:227], v219 offset:26624
	s_waitcnt lgkmcnt(1)
	v_mfma_f32_16x16x32_f16 v[68:71], v[236:239], v[112:115], v[68:71]
	v_mfma_f32_16x16x32_f16 v[80:83], v[236:239], v[116:119], v[80:83]
	ds_read_b128 v[236:239], v219 offset:28672
	s_waitcnt lgkmcnt(1)
	v_mfma_f32_16x16x32_f16 v[56:59], v[224:227], v[112:115], v[56:59]
	v_mfma_f32_16x16x32_f16 v[72:75], v[224:227], v[116:119], v[72:75]
	ds_read_b128 v[224:227], v219 offset:30720
	s_waitcnt lgkmcnt(1)
	v_mfma_f32_16x16x32_f16 v[44:47], v[236:239], v[112:115], v[44:47]
	v_mfma_f32_16x16x32_f16 v[60:63], v[236:239], v[116:119], v[60:63]
	s_waitcnt lgkmcnt(0)
	v_mfma_f32_16x16x32_f16 v[40:43], v[224:227], v[112:115], v[40:43]
	v_cvt_pk_f16_f32 v112, v133, v137
	v_cvt_pk_f16_f32 v113, v135, v139
	v_cvt_pk_f16_f32 v114, v125, v141
	v_mfma_f32_16x16x32_f16 v[48:51], v[224:227], v[116:119], v[48:51]
	v_cvt_pk_f16_f32 v116, v132, v136
	v_cvt_pk_f16_f32 v117, v134, v138
	v_cvt_pk_f16_f32 v118, v124, v140
	v_cvt_pk_f16_f32 v119, v126, v142
	v_cvt_pk_f16_f32 v115, v127, v143
	s_nop 0
	v_mfma_f32_16x16x32_f16 v[84:87], v[220:223], v[116:119], v[84:87]
	v_mfma_f32_16x16x32_f16 v[96:99], v[220:223], v[112:115], v[96:99]
	ds_read_b128 v[220:223], v202 offset:22528
	ds_read_b128 v[240:243], v202 offset:24576
	ds_read_b128 v[244:247], v202 offset:26624
	ds_read_b128 v[248:251], v202 offset:28672
	s_waitcnt lgkmcnt(3)
	v_mfma_f32_16x16x32_f16 v[76:79], v[220:223], v[116:119], v[76:79]
	v_mfma_f32_16x16x32_f16 v[88:91], v[220:223], v[112:115], v[88:91]
	ds_read_b128 v[220:223], v202 offset:30720
	s_waitcnt lgkmcnt(3)
	v_mfma_f32_16x16x32_f16 v[68:71], v[240:243], v[116:119], v[68:71]
	v_mfma_f32_16x16x32_f16 v[80:83], v[240:243], v[112:115], v[80:83]
	ds_read_b128 v[240:243], v202 offset:32768
	s_waitcnt lgkmcnt(3)
	v_mfma_f32_16x16x32_f16 v[56:59], v[244:247], v[116:119], v[56:59]
	v_mfma_f32_16x16x32_f16 v[72:75], v[244:247], v[112:115], v[72:75]
	s_waitcnt lgkmcnt(2)
	v_mfma_f32_16x16x32_f16 v[44:47], v[248:251], v[116:119], v[44:47]
	v_mfma_f32_16x16x32_f16 v[60:63], v[248:251], v[112:115], v[60:63]
	s_waitcnt lgkmcnt(1)
	v_mfma_f32_16x16x32_f16 v[40:43], v[220:223], v[116:119], v[40:43]
	v_mfma_f32_16x16x32_f16 v[48:51], v[220:223], v[112:115], v[48:51]
	v_mfma_f32_16x16x32_f16 v[92:95], v[228:231], v[116:119], v[92:95]
	v_mfma_f32_16x16x32_f16 v[100:103], v[228:231], v[112:115], v[100:103]
	s_waitcnt lgkmcnt(0)
	v_mfma_f32_16x16x32_f16 v[104:107], v[240:243], v[116:119], v[104:107]
	v_mfma_f32_16x16x32_f16 v[108:111], v[240:243], v[112:115], v[108:111]
	s_cbranch_vccnz .LBB0_807
; DI void st_chunk_v(char* sdst, int c, const uint4& v) {
;   const int row = c >> 3, c8 = c & 7, kk = c8 >> 2, cc = c8 & 3, sw = (row >> 1) & 7;
;   const int gq = (cc & 1) * 2, part = cc >> 1;
;   char* base = sdst + row * 128 + part * 8;
;   *(uint2*)(base + (((kk * 4 + gq) ^ sw) << 4)) = make_uint2(v.x, v.y);
;   *(uint2*)(base + (((kk * 4 + gq + 1) ^ sw) << 4)) = make_uint2(v.z, v.w);
; }
; DI void gload2(R2& r, const bf16_t* gsrc, size_t gp, int tid) { r.a = ld_chunk(gsrc, gp, tid); r.b = ld_chunk(gsrc, gp, tid + 256); }
; DI void gload4(R4& r, const bf16_t* gsrc, size_t gp, int tid) { r.a = ld_chunk(gsrc, gp, tid); r.b = ld_chunk(gsrc, gp, tid + 256); r.c = ld_chunk(gsrc, gp, tid + 512); r.d = ld_chunk(gsrc, gp, tid + 768); }
; DI void sstoreK2(const R2& r, char* sdst, int tid) { st_chunk_k(sdst, tid, r.a); st_chunk_k(sdst, tid + 256, r.b); }
; DI void sstoreV2(const R2& r, char* sdst, int tid) { st_chunk_v(sdst, tid, r.a); st_chunk_v(sdst, tid + 256, r.b); }
; DI void sstoreV4(const R4& r, char* sdst, int tid) { st_chunk_v(sdst, tid, r.a); st_chunk_v(sdst, tid + 256, r.b); st_chunk_v(sdst, tid + 512, r.c); st_chunk_v(sdst, tid + 768, r.d); }
; DI void attn_A(const Params& P, int l, int b, int head, int qt, float lam, char* smem, bf16_t* ybase, size_t ypitch) {
;     ...
;     if (n < qt) {
;       char* sn = smem + ((n + 1) & 1) * STAGE;
;       sstoreK2(rk0, sn, tid); sstoreK2(rk1, sn + 9216, tid); sstoreV4(rv, sn + 18432, tid);
;     }
;     __syncthreads();
	s_andn2_b32 s6, 1, s8
	s_mul_i32 s6, s6, 0x9000
	v_add_u32_e32 v112, s6, v155
	v_add_u32_e32 v113, v112, v195
	v_add_u32_e32 v112, v112, v196
	s_waitcnt vmcnt(7)
	ds_write_b128 v113, v[16:19]
	s_waitcnt vmcnt(5)
	ds_write_b128 v113, v[20:23] offset:4096
	ds_write_b128 v113, v[24:27] offset:9216
	s_waitcnt vmcnt(4)
	ds_write_b128 v113, v[28:31] offset:13312
	v_add_u32_e32 v113, v112, v197
	v_add_u32_e32 v112, v112, v198
	s_waitcnt vmcnt(2)
	ds_write2st64_b64 v113, v[32:33], v[36:37] offset0:36 offset1:44
	ds_write2st64_b64 v112, v[34:35], v[38:39] offset0:36 offset1:44
	s_waitcnt vmcnt(0)
	ds_write2st64_b64 v113, v[52:53], v[64:65] offset0:52 offset1:60
	ds_write2st64_b64 v112, v[54:55], v[66:67] offset0:52 offset1:60
	s_branch .LBB0_807
